# K-loop headers aligned to 64 bytes
# speedup vs baseline: 1.0004x; 1.0004x over previous
; template <class Epi, class Sched, bool ALIGN_EPI = false, bool SP2 = false>
; __device__ __forceinline__ void gemm_phase(PG8_LAS unsigned char* lds, const Gemm g, const Sched& S, const Epi& E, const int tid_in) {
;     ...
;     for (;;) {
;         const bool has_next = S.next(ui + 1, nxt);
;         const char* nA = has_next ? (const char*)g.A + (size_t)nxt.pm * tstepA + (size_t)nxt.k0 * 2 : cA; const char* nB = has_next ? (const char*)g.Bt + (size_t)nxt.pn * tstepB + (size_t)nxt.k0 * 2 : cB;
;         for (int t = 0; t < nt; t += 2) {
;             const bool last = (t == nt - 2);
;             const char* a1 = cA + (size_t)(t + 1) * kstep;
;             const char* a2 = last ? nA : cA + (size_t)(t + 2) * kstep; const char* b2 = last ? nB : cB + (size_t)(t + 2) * kstep;
;             const char* a3 = a2 + kstep; const char* b3 = b2 + kstep;
;     ...
; #pragma unroll
;         for (int a = 0; a < 2; ++a)
; #pragma unroll
;             for (int b = 0; b < 2; ++b)
; #pragma unroll
;                 for (int m = 0; m < 4; ++m)
; #pragma unroll
;                     for (int n = 0; n < 2; ++n) acc[a][b][m][n] = (f32x4){0.f, 0.f, 0.f, 0.f};
.LBB0_144:
	s_ashr_i32 s13, s12, 31
	s_lshl_b64 s[14:15], s[12:13], 19
	s_add_u32 s14, s33, s14
	s_addc_u32 s15, s39, s15
	s_and_b64 s[16:17], s[6:7], exec
	s_cselect_b32 s13, s15, s23
	s_cselect_b32 s19, s14, s22
	s_ashr_i32 s11, s10, 31
	s_lshl_b64 s[16:17], s[10:11], 19
	s_add_u32 s16, s40, s16
	s_addc_u32 s17, s41, s17
	s_and_b64 s[30:31], s[6:7], exec
	s_cselect_b32 s11, s17, s29
	s_cselect_b32 s60, s16, s28
	s_add_u32 s22, s22, 0x40080
	s_addc_u32 s23, s23, 0
	s_add_u32 s70, s28, 0x100
	v_mov_b32_e32 v0, 0
	s_addc_u32 s71, s29, 0
	s_mov_b32 s72, -2
	v_mov_b32_e32 v1, v0
	v_mov_b32_e32 v2, v0
	v_mov_b32_e32 v3, v0
	v_mov_b32_e32 v4, v0
	v_mov_b32_e32 v5, v0
	v_mov_b32_e32 v6, v0
	v_mov_b32_e32 v7, v0
	v_mov_b32_e32 v12, v0
	v_mov_b32_e32 v13, v0
	v_mov_b32_e32 v14, v0
	v_mov_b32_e32 v15, v0
	v_mov_b32_e32 v20, v0
	v_mov_b32_e32 v21, v0
	v_mov_b32_e32 v22, v0
	v_mov_b32_e32 v23, v0
	v_mov_b32_e32 v28, v0
	v_mov_b32_e32 v29, v0
	v_mov_b32_e32 v30, v0
	v_mov_b32_e32 v31, v0
	v_mov_b32_e32 v36, v0
	v_mov_b32_e32 v37, v0
	v_mov_b32_e32 v38, v0
	v_mov_b32_e32 v39, v0
	v_mov_b32_e32 v44, v0
	v_mov_b32_e32 v45, v0
	v_mov_b32_e32 v46, v0
	v_mov_b32_e32 v47, v0
	v_mov_b32_e32 v52, v0
	v_mov_b32_e32 v53, v0
	v_mov_b32_e32 v54, v0
	v_mov_b32_e32 v55, v0
	v_mov_b32_e32 v8, v0
	v_mov_b32_e32 v9, v0
	v_mov_b32_e32 v10, v0
	v_mov_b32_e32 v11, v0
	v_mov_b32_e32 v16, v0
	v_mov_b32_e32 v17, v0
	v_mov_b32_e32 v18, v0
	v_mov_b32_e32 v19, v0
	v_mov_b32_e32 v24, v0
	v_mov_b32_e32 v25, v0
	v_mov_b32_e32 v26, v0
	v_mov_b32_e32 v27, v0
	v_mov_b32_e32 v32, v0
	v_mov_b32_e32 v33, v0
	v_mov_b32_e32 v34, v0
	v_mov_b32_e32 v35, v0
	v_mov_b32_e32 v40, v0
	v_mov_b32_e32 v41, v0
	v_mov_b32_e32 v42, v0
	v_mov_b32_e32 v43, v0
	v_mov_b32_e32 v48, v0
	v_mov_b32_e32 v49, v0
	v_mov_b32_e32 v50, v0
	v_mov_b32_e32 v51, v0
	v_mov_b32_e32 v56, v0
	v_mov_b32_e32 v57, v0
	v_mov_b32_e32 v58, v0
	v_mov_b32_e32 v59, v0
	v_mov_b32_e32 v60, v0
	v_mov_b32_e32 v61, v0
	v_mov_b32_e32 v62, v0
	v_mov_b32_e32 v63, v0
	v_mov_b32_e32 v64, v0
	v_mov_b32_e32 v65, v0
	v_mov_b32_e32 v66, v0
	v_mov_b32_e32 v67, v0
	v_mov_b32_e32 v68, v0
	v_mov_b32_e32 v69, v0
	v_mov_b32_e32 v70, v0
	v_mov_b32_e32 v71, v0
	v_mov_b32_e32 v76, v0
	v_mov_b32_e32 v77, v0
	v_mov_b32_e32 v78, v0
	v_mov_b32_e32 v79, v0
	v_mov_b32_e32 v84, v0
	v_mov_b32_e32 v85, v0
	v_mov_b32_e32 v86, v0
	v_mov_b32_e32 v87, v0
	v_mov_b32_e32 v92, v0
	v_mov_b32_e32 v93, v0
	v_mov_b32_e32 v94, v0
	v_mov_b32_e32 v95, v0
	v_mov_b32_e32 v102, v0
	v_mov_b32_e32 v103, v0
	v_mov_b32_e32 v104, v0
	v_mov_b32_e32 v105, v0
	v_mov_b32_e32 v110, v0
	v_mov_b32_e32 v111, v0
	v_mov_b32_e32 v112, v0
	v_mov_b32_e32 v113, v0
	v_mov_b32_e32 v118, v0
	v_mov_b32_e32 v119, v0
	v_mov_b32_e32 v120, v0
	v_mov_b32_e32 v121, v0
	v_mov_b32_e32 v72, v0
	v_mov_b32_e32 v73, v0
	v_mov_b32_e32 v74, v0
	v_mov_b32_e32 v75, v0
	v_mov_b32_e32 v80, v0
	v_mov_b32_e32 v81, v0
	v_mov_b32_e32 v82, v0
	v_mov_b32_e32 v83, v0
	v_mov_b32_e32 v88, v0
	v_mov_b32_e32 v89, v0
	v_mov_b32_e32 v90, v0
	v_mov_b32_e32 v91, v0
	v_mov_b32_e32 v98, v0
	v_mov_b32_e32 v99, v0
	v_mov_b32_e32 v100, v0
	v_mov_b32_e32 v101, v0
	v_mov_b32_e32 v106, v0
	v_mov_b32_e32 v107, v0
	v_mov_b32_e32 v108, v0
	v_mov_b32_e32 v109, v0
	v_mov_b32_e32 v114, v0
	v_mov_b32_e32 v115, v0
	v_mov_b32_e32 v116, v0
	v_mov_b32_e32 v117, v0
	v_mov_b32_e32 v122, v0
	v_mov_b32_e32 v123, v0
	v_mov_b32_e32 v124, v0
	v_mov_b32_e32 v125, v0
	v_mov_b32_e32 v126, v0
	v_mov_b32_e32 v127, v0
	v_mov_b32_e32 v128, v0
	v_mov_b32_e32 v129, v0
	.p2align 6

; template <class Epi, class Sched, bool ALIGN_EPI = false, bool SP2 = false>
; __device__ __forceinline__ void gemm_phase(PG8_LAS unsigned char* lds, const Gemm g, const Sched& S, const Epi& E, const int tid_in) {
;     ...
;     for (;;) {
;         const bool has_next = S.next(ui + 1, nxt);
;         const char* nA = has_next ? (const char*)g.A + (size_t)nxt.pm * tstepA + (size_t)nxt.k0 * 2 : cA; const char* nB = has_next ? (const char*)g.Bt + (size_t)nxt.pn * tstepB + (size_t)nxt.k0 * 2 : cB;
;         for (int t = 0; t < nt; t += 2) {
;             const bool last = (t == nt - 2);
;             const char* a1 = cA + (size_t)(t + 1) * kstep;
;             const char* a2 = last ? nA : cA + (size_t)(t + 2) * kstep; const char* b2 = last ? nB : cB + (size_t)(t + 2) * kstep;
;             const char* a3 = a2 + kstep; const char* b3 = b2 + kstep;
;     ...
; #pragma unroll
;         for (int a = 0; a < 2; ++a)
; #pragma unroll
;             for (int b = 0; b < 2; ++b)
; #pragma unroll
;                 for (int m = 0; m < 4; ++m)
; #pragma unroll
;                     for (int n = 0; n < 2; ++n) acc[a][b][m][n] = (f32x4){0.f, 0.f, 0.f, 0.f};
.LBB0_212:
	s_ashr_i32 s13, s12, 31
	s_lshl_b64 s[14:15], s[12:13], 19
	s_add_u32 s14, s88, s14
	s_addc_u32 s15, s89, s15
	s_and_b64 s[16:17], s[6:7], exec
	s_cselect_b32 s13, s15, s21
	s_cselect_b32 s54, s14, s20
	s_ashr_i32 s11, s10, 31
	s_lshl_b64 s[16:17], s[10:11], 19
	s_add_u32 s16, s31, s16
	s_addc_u32 s17, s33, s17
	s_and_b64 s[28:29], s[6:7], exec
	s_cselect_b32 s11, s17, s23
	s_cselect_b32 s55, s16, s22
	s_add_u32 s20, s20, 0x40080
	s_addc_u32 s21, s21, 0
	s_add_u32 s56, s22, 0x100
	v_mov_b32_e32 v0, 0
	s_addc_u32 s60, s23, 0
	s_mov_b32 s70, -2
	v_mov_b32_e32 v1, v0
	v_mov_b32_e32 v2, v0
	v_mov_b32_e32 v3, v0
	v_mov_b32_e32 v8, v0
	v_mov_b32_e32 v9, v0
	v_mov_b32_e32 v10, v0
	v_mov_b32_e32 v11, v0
	v_mov_b32_e32 v16, v0
	v_mov_b32_e32 v17, v0
	v_mov_b32_e32 v18, v0
	v_mov_b32_e32 v19, v0
	v_mov_b32_e32 v24, v0
	v_mov_b32_e32 v25, v0
	v_mov_b32_e32 v26, v0
	v_mov_b32_e32 v27, v0
	v_mov_b32_e32 v32, v0
	v_mov_b32_e32 v33, v0
	v_mov_b32_e32 v34, v0
	v_mov_b32_e32 v35, v0
	v_mov_b32_e32 v40, v0
	v_mov_b32_e32 v41, v0
	v_mov_b32_e32 v42, v0
	v_mov_b32_e32 v43, v0
	v_mov_b32_e32 v48, v0
	v_mov_b32_e32 v49, v0
	v_mov_b32_e32 v50, v0
	v_mov_b32_e32 v51, v0
	v_mov_b32_e32 v56, v0
	v_mov_b32_e32 v57, v0
	v_mov_b32_e32 v58, v0
	v_mov_b32_e32 v59, v0
	v_mov_b32_e32 v4, v0
	v_mov_b32_e32 v5, v0
	v_mov_b32_e32 v6, v0
	v_mov_b32_e32 v7, v0
	v_mov_b32_e32 v12, v0
	v_mov_b32_e32 v13, v0
	v_mov_b32_e32 v14, v0
	v_mov_b32_e32 v15, v0
	v_mov_b32_e32 v20, v0
	v_mov_b32_e32 v21, v0
	v_mov_b32_e32 v22, v0
	v_mov_b32_e32 v23, v0
	v_mov_b32_e32 v28, v0
	v_mov_b32_e32 v29, v0
	v_mov_b32_e32 v30, v0
	v_mov_b32_e32 v31, v0
	v_mov_b32_e32 v36, v0
	v_mov_b32_e32 v37, v0
	v_mov_b32_e32 v38, v0
	v_mov_b32_e32 v39, v0
	v_mov_b32_e32 v44, v0
	v_mov_b32_e32 v45, v0
	v_mov_b32_e32 v46, v0
	v_mov_b32_e32 v47, v0
	v_mov_b32_e32 v52, v0
	v_mov_b32_e32 v53, v0
	v_mov_b32_e32 v54, v0
	v_mov_b32_e32 v55, v0
	v_mov_b32_e32 v60, v0
	v_mov_b32_e32 v61, v0
	v_mov_b32_e32 v62, v0
	v_mov_b32_e32 v63, v0
	v_mov_b32_e32 v64, v0
	v_mov_b32_e32 v65, v0
	v_mov_b32_e32 v66, v0
	v_mov_b32_e32 v67, v0
	v_mov_b32_e32 v72, v0
	v_mov_b32_e32 v73, v0
	v_mov_b32_e32 v74, v0
	v_mov_b32_e32 v75, v0
	v_mov_b32_e32 v80, v0
	v_mov_b32_e32 v81, v0
	v_mov_b32_e32 v82, v0
	v_mov_b32_e32 v83, v0
	v_mov_b32_e32 v88, v0
	v_mov_b32_e32 v89, v0
	v_mov_b32_e32 v90, v0
	v_mov_b32_e32 v91, v0
	v_mov_b32_e32 v98, v0
	v_mov_b32_e32 v99, v0
	v_mov_b32_e32 v100, v0
	v_mov_b32_e32 v101, v0
	v_mov_b32_e32 v106, v0
	v_mov_b32_e32 v107, v0
	v_mov_b32_e32 v108, v0
	v_mov_b32_e32 v109, v0
	v_mov_b32_e32 v114, v0
	v_mov_b32_e32 v115, v0
	v_mov_b32_e32 v116, v0
	v_mov_b32_e32 v117, v0
	v_mov_b32_e32 v122, v0
	v_mov_b32_e32 v123, v0
	v_mov_b32_e32 v124, v0
	v_mov_b32_e32 v125, v0
	v_mov_b32_e32 v68, v0
	v_mov_b32_e32 v69, v0
	v_mov_b32_e32 v70, v0
	v_mov_b32_e32 v71, v0
	v_mov_b32_e32 v76, v0
	v_mov_b32_e32 v77, v0
	v_mov_b32_e32 v78, v0
	v_mov_b32_e32 v79, v0
	v_mov_b32_e32 v84, v0
	v_mov_b32_e32 v85, v0
	v_mov_b32_e32 v86, v0
	v_mov_b32_e32 v87, v0
	v_mov_b32_e32 v92, v0
	v_mov_b32_e32 v93, v0
	v_mov_b32_e32 v94, v0
	v_mov_b32_e32 v95, v0
	v_mov_b32_e32 v102, v0
	v_mov_b32_e32 v103, v0
	v_mov_b32_e32 v104, v0
	v_mov_b32_e32 v105, v0
	v_mov_b32_e32 v110, v0
	v_mov_b32_e32 v111, v0
	v_mov_b32_e32 v112, v0
	v_mov_b32_e32 v113, v0
	v_mov_b32_e32 v118, v0
	v_mov_b32_e32 v119, v0
	v_mov_b32_e32 v120, v0
	v_mov_b32_e32 v121, v0
	v_mov_b32_e32 v126, v0
	v_mov_b32_e32 v127, v0
	v_mov_b32_e32 v128, v0
	v_mov_b32_e32 v129, v0
	.p2align 6

; template <class Epi, class Sched, bool ALIGN_EPI = false, bool SP2 = false>
; __device__ __forceinline__ void gemm_phase(PG8_LAS unsigned char* lds, const Gemm g, const Sched& S, const Epi& E, const int tid_in) {
;     ...
;     for (;;) {
;         const bool has_next = S.next(ui + 1, nxt);
;         const char* nA = has_next ? (const char*)g.A + (size_t)nxt.pm * tstepA + (size_t)nxt.k0 * 2 : cA; const char* nB = has_next ? (const char*)g.Bt + (size_t)nxt.pn * tstepB + (size_t)nxt.k0 * 2 : cB;
;         for (int t = 0; t < nt; t += 2) {
;             const bool last = (t == nt - 2);
;             const char* a1 = cA + (size_t)(t + 1) * kstep;
;             const char* a2 = last ? nA : cA + (size_t)(t + 2) * kstep; const char* b2 = last ? nB : cB + (size_t)(t + 2) * kstep;
;             const char* a3 = a2 + kstep; const char* b3 = b2 + kstep;
;     ...
; #pragma unroll
;         for (int a = 0; a < 2; ++a)
; #pragma unroll
;             for (int b = 0; b < 2; ++b)
; #pragma unroll
;                 for (int m = 0; m < 4; ++m)
; #pragma unroll
;                     for (int n = 0; n < 2; ++n) acc[a][b][m][n] = (f32x4){0.f, 0.f, 0.f, 0.f};
.LBB0_248:
	s_ashr_i32 s11, s10, 31
	s_lshl_b64 s[12:13], s[10:11], 19
	s_add_u32 s12, s88, s12
	s_addc_u32 s13, s89, s13
	s_and_b64 s[14:15], s[6:7], exec
	s_cselect_b32 s11, s13, s19
	s_cselect_b32 s55, s12, s18
	s_ashr_i32 s9, s8, 31
	s_lshl_b64 s[14:15], s[8:9], 19
	s_add_u32 s14, s28, s14
	s_addc_u32 s15, s29, s15
	s_and_b64 s[22:23], s[6:7], exec
	s_cselect_b32 s9, s15, s21
	s_cselect_b32 s60, s14, s20
	s_add_u32 s18, s18, 0x40080
	s_addc_u32 s19, s19, 0
	s_add_u32 s70, s20, 0x100
	v_mov_b32_e32 v0, 0
	s_addc_u32 s71, s21, 0
	s_mov_b32 s72, -2
	v_mov_b32_e32 v1, v0
	v_mov_b32_e32 v2, v0
	v_mov_b32_e32 v3, v0
	v_mov_b32_e32 v4, v0
	v_mov_b32_e32 v5, v0
	v_mov_b32_e32 v6, v0
	v_mov_b32_e32 v7, v0
	v_mov_b32_e32 v8, v0
	v_mov_b32_e32 v9, v0
	v_mov_b32_e32 v10, v0
	v_mov_b32_e32 v11, v0
	v_mov_b32_e32 v20, v0
	v_mov_b32_e32 v21, v0
	v_mov_b32_e32 v22, v0
	v_mov_b32_e32 v23, v0
	v_mov_b32_e32 v24, v0
	v_mov_b32_e32 v25, v0
	v_mov_b32_e32 v26, v0
	v_mov_b32_e32 v27, v0
	v_mov_b32_e32 v36, v0
	v_mov_b32_e32 v37, v0
	v_mov_b32_e32 v38, v0
	v_mov_b32_e32 v39, v0
	v_mov_b32_e32 v40, v0
	v_mov_b32_e32 v41, v0
	v_mov_b32_e32 v42, v0
	v_mov_b32_e32 v43, v0
	v_mov_b32_e32 v52, v0
	v_mov_b32_e32 v53, v0
	v_mov_b32_e32 v54, v0
	v_mov_b32_e32 v55, v0
	v_mov_b32_e32 v12, v0
	v_mov_b32_e32 v13, v0
	v_mov_b32_e32 v14, v0
	v_mov_b32_e32 v15, v0
	v_mov_b32_e32 v16, v0
	v_mov_b32_e32 v17, v0
	v_mov_b32_e32 v18, v0
	v_mov_b32_e32 v19, v0
	v_mov_b32_e32 v28, v0
	v_mov_b32_e32 v29, v0
	v_mov_b32_e32 v30, v0
	v_mov_b32_e32 v31, v0
	v_mov_b32_e32 v32, v0
	v_mov_b32_e32 v33, v0
	v_mov_b32_e32 v34, v0
	v_mov_b32_e32 v35, v0
	v_mov_b32_e32 v44, v0
	v_mov_b32_e32 v45, v0
	v_mov_b32_e32 v46, v0
	v_mov_b32_e32 v47, v0
	v_mov_b32_e32 v48, v0
	v_mov_b32_e32 v49, v0
	v_mov_b32_e32 v50, v0
	v_mov_b32_e32 v51, v0
	v_mov_b32_e32 v56, v0
	v_mov_b32_e32 v57, v0
	v_mov_b32_e32 v58, v0
	v_mov_b32_e32 v59, v0
	v_mov_b32_e32 v60, v0
	v_mov_b32_e32 v61, v0
	v_mov_b32_e32 v62, v0
	v_mov_b32_e32 v63, v0
	v_mov_b32_e32 v64, v0
	v_mov_b32_e32 v65, v0
	v_mov_b32_e32 v66, v0
	v_mov_b32_e32 v67, v0
	v_mov_b32_e32 v68, v0
	v_mov_b32_e32 v69, v0
	v_mov_b32_e32 v70, v0
	v_mov_b32_e32 v71, v0
	v_mov_b32_e32 v72, v0
	v_mov_b32_e32 v73, v0
	v_mov_b32_e32 v74, v0
	v_mov_b32_e32 v75, v0
	v_mov_b32_e32 v84, v0
	v_mov_b32_e32 v85, v0
	v_mov_b32_e32 v86, v0
	v_mov_b32_e32 v87, v0
	v_mov_b32_e32 v88, v0
	v_mov_b32_e32 v89, v0
	v_mov_b32_e32 v90, v0
	v_mov_b32_e32 v91, v0
	v_mov_b32_e32 v102, v0
	v_mov_b32_e32 v103, v0
	v_mov_b32_e32 v104, v0
	v_mov_b32_e32 v105, v0
	v_mov_b32_e32 v106, v0
	v_mov_b32_e32 v107, v0
	v_mov_b32_e32 v108, v0
	v_mov_b32_e32 v109, v0
	v_mov_b32_e32 v118, v0
	v_mov_b32_e32 v119, v0
	v_mov_b32_e32 v120, v0
	v_mov_b32_e32 v121, v0
	v_mov_b32_e32 v76, v0
	v_mov_b32_e32 v77, v0
	v_mov_b32_e32 v78, v0
	v_mov_b32_e32 v79, v0
	v_mov_b32_e32 v80, v0
	v_mov_b32_e32 v81, v0
	v_mov_b32_e32 v82, v0
	v_mov_b32_e32 v83, v0
	v_mov_b32_e32 v92, v0
	v_mov_b32_e32 v93, v0
	v_mov_b32_e32 v94, v0
	v_mov_b32_e32 v95, v0
	v_mov_b32_e32 v98, v0
	v_mov_b32_e32 v99, v0
	v_mov_b32_e32 v100, v0
	v_mov_b32_e32 v101, v0
	v_mov_b32_e32 v110, v0
	v_mov_b32_e32 v111, v0
	v_mov_b32_e32 v112, v0
	v_mov_b32_e32 v113, v0
	v_mov_b32_e32 v114, v0
	v_mov_b32_e32 v115, v0
	v_mov_b32_e32 v116, v0
	v_mov_b32_e32 v117, v0
	v_mov_b32_e32 v122, v0
	v_mov_b32_e32 v123, v0
	v_mov_b32_e32 v124, v0
	v_mov_b32_e32 v125, v0
	v_mov_b32_e32 v126, v0
	v_mov_b32_e32 v127, v0
	v_mov_b32_e32 v128, v0
	v_mov_b32_e32 v129, v0
	.p2align 6

; DI void norm_phase(const float* xp, const float* xs, const float* gvec, const float* MODL  , int sc_off, bf16_t* H, int tid,
;                    const float* P, int nparts, const float* pgate, float* X) {
;     ...
;     for (int it = gw; it < M; it += NGW) {
;         const int row = it < MS ? MP + it : it - MS;
;         const int bi = batch_of(row);
;         const float* xr = (row < MP ? xp : xs) + (size_t)row * 1024; const float* mr = MODL + (size_t)bi * NMOD;
.LBB0_266:
	s_add_i32 s44, s44, s51
	s_mov_b64 s[6:7], 0
	.p2align 6

; #define PG8_BAR __builtin_amdgcn_s_barrier()
; template <class Epi, class Sched, bool ALIGN_EPI = false, bool SP2 = false>
; __device__ __forceinline__ void gemm_phase(PG8_LAS unsigned char* lds, const Gemm g, const Sched& S, const Epi& E, const int tid_in) {
;     ...
;         for (int t = 0; t < nt; t += 2) {
;             const bool last = (t == nt - 2);
;             const char* a1 = cA + (size_t)(t + 1) * kstep;
;             const char* a2 = last ? nA : cA + (size_t)(t + 2) * kstep; const char* b2 = last ? nB : cB + (size_t)(t + 2) * kstep;
;             const char* a3 = a2 + kstep; const char* b3 = b2 + kstep;
;             if (last && has_next) S.a_ready(nxt);
;             if constexpr (SP2) {
;             PG8_LDB(B0, 0, 0); PG8_LDB(B1, 0, 1); PG8_SCHED; PG8_LDA(At, 0, 0); PG8_STAGE(PG8_SA(1, 1), a1 + hstepA, voffA);
;             PG8_WAIT_V(8); PG8_WAIT_L(0); PG8_BAR; PG8_MMA(0, 0, At, B0); PG8_MMA(0, 1, At, B1); PG8_BAR; PG8_SCHED;
;             PG8_LDA(At, 0, 1); PG8_STAGE(PG8_SB(0, 0), b2, voffB); PG8_STAGE(PG8_SB(0, 1), b2 + hstepB, voffB); PG8_STAGE(PG8_SA(0, 0), a2, voffA);
;             PG8_WAIT_V(8); PG8_WAIT_L(0); PG8_BAR; PG8_MMA(1, 0, At, B0); PG8_MMA(1, 1, At, B1); PG8_BAR; PG8_SCHED;
;             PG8_LDB(B0, 1, 0); PG8_LDB(B1, 1, 1); PG8_SCHED; PG8_LDA(At, 1, 0); PG8_STAGE(PG8_SA(0, 1), a2 + hstepA, voffA);
;             PG8_WAIT_V(8); PG8_WAIT_L(0); PG8_BAR; PG8_MMA(0, 0, At, B0); PG8_MMA(0, 1, At, B1); PG8_BAR; PG8_SCHED;
;             PG8_LDA(At, 1, 1); PG8_STAGE(PG8_SB(1, 0), b3, voffB); PG8_STAGE(PG8_SB(1, 1), b3 + hstepB, voffB); PG8_STAGE(PG8_SA(1, 0), a3, voffA);
;             PG8_WAIT_V(8); PG8_WAIT_L(0); PG8_BAR; PG8_MMA(1, 0, At, B0); PG8_MMA(1, 1, At, B1); PG8_BAR; PG8_SCHED;
;             } else {
;             PG8_LDB(B0, 0, 0); PG8_SCHED; PG8_LDA(At, 0, 0); PG8_STAGE(PG8_SA(1, 1), a1 + hstepA, voffA);
;             PG8_WAIT_L(8); PG8_BAR; PG8_WAIT_L(0); PG8_MMA(0, 0, At, B0); PG8_BAR; PG8_SCHED;
;             PG8_LDB(B1, 0, 1); PG8_STAGE(PG8_SB(0, 0), b2, voffB);
;             PG8_BAR; PG8_WAIT_L(0); PG8_MMA(0, 1, At, B1); PG8_BAR;
;             PG8_LDA(At, 0, 1); PG8_STAGE(PG8_SA(0, 0), a2, voffA);
;             PG8_BAR; PG8_WAIT_L(0); PG8_MMA(1, 0, At, B0); PG8_BAR; PG8_SCHED;
;             PG8_STAGE(PG8_SB(0, 1), b2 + hstepB, voffB);
;             PG8_WAIT_V(6); PG8_BAR; PG8_MMA(1, 1, At, B1); PG8_BAR;
.Lmz_keep:
	.p2align 6

; DI void norm_phase(const float* xp, const float* xs, const float* gvec, const float* MODL  , int sc_off, bf16_t* H, int tid,
;                    const float* P, int nparts, const float* pgate, float* X) {
;     ...
;     for (int it = gw; it < M; it += NGW) {
;         const int row = it < MS ? MP + it : it - MS;
;         const int bi = batch_of(row);
;         const float* xr = (row < MP ? xp : xs) + (size_t)row * 1024; const float* mr = MODL + (size_t)bi * NMOD;
.LBB0_434:
	s_add_i32 s56, s56, s51
	s_mov_b64 s[20:21], 0
	.p2align 6

; template <class Epi, class Sched, bool ALIGN_EPI = false, bool SP2 = false>
; __device__ __forceinline__ void gemm_phase(PG8_LAS unsigned char* lds, const Gemm g, const Sched& S, const Epi& E, const int tid_in) {
;     ...
;     for (;;) {
;         const bool has_next = S.next(ui + 1, nxt);
;         const char* nA = has_next ? (const char*)g.A + (size_t)nxt.pm * tstepA + (size_t)nxt.k0 * 2 : cA; const char* nB = has_next ? (const char*)g.Bt + (size_t)nxt.pn * tstepB + (size_t)nxt.k0 * 2 : cB;
;         for (int t = 0; t < nt; t += 2) {
;             const bool last = (t == nt - 2);
;             const char* a1 = cA + (size_t)(t + 1) * kstep;
;             const char* a2 = last ? nA : cA + (size_t)(t + 2) * kstep; const char* b2 = last ? nB : cB + (size_t)(t + 2) * kstep;
;             const char* a3 = a2 + kstep; const char* b3 = b2 + kstep;
;     ...
; #pragma unroll
;         for (int a = 0; a < 2; ++a)
; #pragma unroll
;             for (int b = 0; b < 2; ++b)
; #pragma unroll
;                 for (int m = 0; m < 4; ++m)
; #pragma unroll
;                     for (int n = 0; n < 2; ++n) acc[a][b][m][n] = (f32x4){0.f, 0.f, 0.f, 0.f};
.LBB0_467:
	s_ashr_i32 s13, s12, 31
	s_lshl_b64 s[14:15], s[12:13], 18
	s_add_u32 s14, s0, s14
	s_addc_u32 s15, s1, s15
	s_and_b64 s[16:17], s[6:7], exec
	s_cselect_b32 s13, s15, s21
	s_cselect_b32 s54, s14, s20
	s_ashr_i32 s11, s10, 31
	s_lshl_b64 s[16:17], s[10:11], 18
	s_add_u32 s16, s31, s16
	s_addc_u32 s17, s33, s17
	s_and_b64 s[28:29], s[6:7], exec
	s_cselect_b32 s11, s17, s23
	s_cselect_b32 s55, s16, s22
	s_add_u32 s20, s20, 0x20080
	s_addc_u32 s21, s21, 0
	s_add_u32 s56, s22, 0x100
	v_mov_b32_e32 v0, 0
	s_addc_u32 s60, s23, 0
	s_mov_b32 s70, -2
	v_mov_b32_e32 v1, v0
	v_mov_b32_e32 v2, v0
	v_mov_b32_e32 v3, v0
	v_mov_b32_e32 v4, v0
	v_mov_b32_e32 v5, v0
	v_mov_b32_e32 v6, v0
	v_mov_b32_e32 v7, v0
	v_mov_b32_e32 v16, v0
	v_mov_b32_e32 v17, v0
	v_mov_b32_e32 v18, v0
	v_mov_b32_e32 v19, v0
	v_mov_b32_e32 v20, v0
	v_mov_b32_e32 v21, v0
	v_mov_b32_e32 v22, v0
	v_mov_b32_e32 v23, v0
	v_mov_b32_e32 v32, v0
	v_mov_b32_e32 v33, v0
	v_mov_b32_e32 v34, v0
	v_mov_b32_e32 v35, v0
	v_mov_b32_e32 v36, v0
	v_mov_b32_e32 v37, v0
	v_mov_b32_e32 v38, v0
	v_mov_b32_e32 v39, v0
	v_mov_b32_e32 v48, v0
	v_mov_b32_e32 v49, v0
	v_mov_b32_e32 v50, v0
	v_mov_b32_e32 v51, v0
	v_mov_b32_e32 v52, v0
	v_mov_b32_e32 v53, v0
	v_mov_b32_e32 v54, v0
	v_mov_b32_e32 v55, v0
	v_mov_b32_e32 v8, v0
	v_mov_b32_e32 v9, v0
	v_mov_b32_e32 v10, v0
	v_mov_b32_e32 v11, v0
	v_mov_b32_e32 v12, v0
	v_mov_b32_e32 v13, v0
	v_mov_b32_e32 v14, v0
	v_mov_b32_e32 v15, v0
	v_mov_b32_e32 v24, v0
	v_mov_b32_e32 v25, v0
	v_mov_b32_e32 v26, v0
	v_mov_b32_e32 v27, v0
	v_mov_b32_e32 v28, v0
	v_mov_b32_e32 v29, v0
	v_mov_b32_e32 v30, v0
	v_mov_b32_e32 v31, v0
	v_mov_b32_e32 v40, v0
	v_mov_b32_e32 v41, v0
	v_mov_b32_e32 v42, v0
	v_mov_b32_e32 v43, v0
	v_mov_b32_e32 v44, v0
	v_mov_b32_e32 v45, v0
	v_mov_b32_e32 v46, v0
	v_mov_b32_e32 v47, v0
	v_mov_b32_e32 v56, v0
	v_mov_b32_e32 v57, v0
	v_mov_b32_e32 v58, v0
	v_mov_b32_e32 v59, v0
	v_mov_b32_e32 v60, v0
	v_mov_b32_e32 v61, v0
	v_mov_b32_e32 v62, v0
	v_mov_b32_e32 v63, v0
	v_mov_b32_e32 v64, v0
	v_mov_b32_e32 v65, v0
	v_mov_b32_e32 v66, v0
	v_mov_b32_e32 v67, v0
	v_mov_b32_e32 v68, v0
	v_mov_b32_e32 v69, v0
	v_mov_b32_e32 v70, v0
	v_mov_b32_e32 v71, v0
	v_mov_b32_e32 v80, v0
	v_mov_b32_e32 v81, v0
	v_mov_b32_e32 v82, v0
	v_mov_b32_e32 v83, v0
	v_mov_b32_e32 v84, v0
	v_mov_b32_e32 v85, v0
	v_mov_b32_e32 v86, v0
	v_mov_b32_e32 v87, v0
	v_mov_b32_e32 v98, v0
	v_mov_b32_e32 v99, v0
	v_mov_b32_e32 v100, v0
	v_mov_b32_e32 v101, v0
	v_mov_b32_e32 v102, v0
	v_mov_b32_e32 v103, v0
	v_mov_b32_e32 v104, v0
	v_mov_b32_e32 v105, v0
	v_mov_b32_e32 v114, v0
	v_mov_b32_e32 v115, v0
	v_mov_b32_e32 v116, v0
	v_mov_b32_e32 v117, v0
	v_mov_b32_e32 v118, v0
	v_mov_b32_e32 v119, v0
	v_mov_b32_e32 v120, v0
	v_mov_b32_e32 v121, v0
	v_mov_b32_e32 v72, v0
	v_mov_b32_e32 v73, v0
	v_mov_b32_e32 v74, v0
	v_mov_b32_e32 v75, v0
	v_mov_b32_e32 v76, v0
	v_mov_b32_e32 v77, v0
	v_mov_b32_e32 v78, v0
	v_mov_b32_e32 v79, v0
	v_mov_b32_e32 v88, v0
	v_mov_b32_e32 v89, v0
	v_mov_b32_e32 v90, v0
	v_mov_b32_e32 v91, v0
	v_mov_b32_e32 v92, v0
	v_mov_b32_e32 v93, v0
	v_mov_b32_e32 v94, v0
	v_mov_b32_e32 v95, v0
	v_mov_b32_e32 v106, v0
	v_mov_b32_e32 v107, v0
	v_mov_b32_e32 v108, v0
	v_mov_b32_e32 v109, v0
	v_mov_b32_e32 v110, v0
	v_mov_b32_e32 v111, v0
	v_mov_b32_e32 v112, v0
	v_mov_b32_e32 v113, v0
	v_mov_b32_e32 v122, v0
	v_mov_b32_e32 v123, v0
	v_mov_b32_e32 v124, v0
	v_mov_b32_e32 v125, v0
	v_mov_b32_e32 v126, v0
	v_mov_b32_e32 v127, v0
	v_mov_b32_e32 v128, v0
	v_mov_b32_e32 v129, v0
	.p2align 6

; template <class Epi, class Sched, bool ALIGN_EPI = false, bool SP2 = false>
; __device__ __forceinline__ void gemm_phase(PG8_LAS unsigned char* lds, const Gemm g, const Sched& S, const Epi& E, const int tid_in) {
;     ...
;     for (;;) {
;         const bool has_next = S.next(ui + 1, nxt);
;         const char* nA = has_next ? (const char*)g.A + (size_t)nxt.pm * tstepA + (size_t)nxt.k0 * 2 : cA; const char* nB = has_next ? (const char*)g.Bt + (size_t)nxt.pn * tstepB + (size_t)nxt.k0 * 2 : cB;
;         for (int t = 0; t < nt; t += 2) {
;             const bool last = (t == nt - 2);
;             const char* a1 = cA + (size_t)(t + 1) * kstep;
;             const char* a2 = last ? nA : cA + (size_t)(t + 2) * kstep; const char* b2 = last ? nB : cB + (size_t)(t + 2) * kstep;
;             const char* a3 = a2 + kstep; const char* b3 = b2 + kstep;
;     ...
; #pragma unroll
;         for (int a = 0; a < 2; ++a)
; #pragma unroll
;             for (int b = 0; b < 2; ++b)
; #pragma unroll
;                 for (int m = 0; m < 4; ++m)
; #pragma unroll
;                     for (int n = 0; n < 2; ++n) acc[a][b][m][n] = (f32x4){0.f, 0.f, 0.f, 0.f};
.LBB0_1026:
	s_ashr_i32 s75, s74, 31
	s_lshl_b64 s[2:3], s[74:75], 19
	s_add_u32 s2, s88, s2
	s_addc_u32 s3, s89, s3
	s_and_b64 s[20:21], s[12:13], exec
	s_cselect_b32 s1, s3, s17
	s_cselect_b32 s15, s2, s16
	s_ashr_i32 s53, s52, 31
	s_lshl_b64 s[20:21], s[52:53], 19
	v_readlane_b32 s28, v254, 52
	s_add_u32 s42, s28, s20
	v_readlane_b32 s20, v254, 53
	s_addc_u32 s43, s20, s21
	s_and_b64 s[20:21], s[12:13], exec
	s_cselect_b32 s28, s43, s19
	s_cselect_b32 s29, s42, s18
	s_add_u32 s16, s16, 0x40080
	s_addc_u32 s17, s17, 0
	s_add_u32 s53, s18, 0x100
	v_mov_b32_e32 v0, 0
	s_addc_u32 s56, s19, 0
	s_mov_b32 s70, -2
	v_mov_b32_e32 v1, v0
	v_mov_b32_e32 v2, v0
	v_mov_b32_e32 v3, v0
	v_mov_b32_e32 v4, v0
	v_mov_b32_e32 v5, v0
	v_mov_b32_e32 v6, v0
	v_mov_b32_e32 v7, v0
	v_mov_b32_e32 v16, v0
	v_mov_b32_e32 v17, v0
	v_mov_b32_e32 v18, v0
	v_mov_b32_e32 v19, v0
	v_mov_b32_e32 v20, v0
	v_mov_b32_e32 v21, v0
	v_mov_b32_e32 v22, v0
	v_mov_b32_e32 v23, v0
	v_mov_b32_e32 v32, v0
	v_mov_b32_e32 v33, v0
	v_mov_b32_e32 v34, v0
	v_mov_b32_e32 v35, v0
	v_mov_b32_e32 v36, v0
	v_mov_b32_e32 v37, v0
	v_mov_b32_e32 v38, v0
	v_mov_b32_e32 v39, v0
	v_mov_b32_e32 v48, v0
	v_mov_b32_e32 v49, v0
	v_mov_b32_e32 v50, v0
	v_mov_b32_e32 v51, v0
	v_mov_b32_e32 v52, v0
	v_mov_b32_e32 v53, v0
	v_mov_b32_e32 v54, v0
	v_mov_b32_e32 v55, v0
	v_mov_b32_e32 v8, v0
	v_mov_b32_e32 v9, v0
	v_mov_b32_e32 v10, v0
	v_mov_b32_e32 v11, v0
	v_mov_b32_e32 v12, v0
	v_mov_b32_e32 v13, v0
	v_mov_b32_e32 v14, v0
	v_mov_b32_e32 v15, v0
	v_mov_b32_e32 v24, v0
	v_mov_b32_e32 v25, v0
	v_mov_b32_e32 v26, v0
	v_mov_b32_e32 v27, v0
	v_mov_b32_e32 v28, v0
	v_mov_b32_e32 v29, v0
	v_mov_b32_e32 v30, v0
	v_mov_b32_e32 v31, v0
	v_mov_b32_e32 v40, v0
	v_mov_b32_e32 v41, v0
	v_mov_b32_e32 v42, v0
	v_mov_b32_e32 v43, v0
	v_mov_b32_e32 v44, v0
	v_mov_b32_e32 v45, v0
	v_mov_b32_e32 v46, v0
	v_mov_b32_e32 v47, v0
	v_mov_b32_e32 v56, v0
	v_mov_b32_e32 v57, v0
	v_mov_b32_e32 v58, v0
	v_mov_b32_e32 v59, v0
	v_mov_b32_e32 v60, v0
	v_mov_b32_e32 v61, v0
	v_mov_b32_e32 v62, v0
	v_mov_b32_e32 v63, v0
	v_mov_b32_e32 v64, v0
	v_mov_b32_e32 v65, v0
	v_mov_b32_e32 v66, v0
	v_mov_b32_e32 v67, v0
	v_mov_b32_e32 v68, v0
	v_mov_b32_e32 v69, v0
	v_mov_b32_e32 v70, v0
	v_mov_b32_e32 v71, v0
	v_mov_b32_e32 v80, v0
	v_mov_b32_e32 v81, v0
	v_mov_b32_e32 v82, v0
	v_mov_b32_e32 v83, v0
	v_mov_b32_e32 v84, v0
	v_mov_b32_e32 v85, v0
	v_mov_b32_e32 v86, v0
	v_mov_b32_e32 v87, v0
	v_mov_b32_e32 v98, v0
	v_mov_b32_e32 v99, v0
	v_mov_b32_e32 v100, v0
	v_mov_b32_e32 v101, v0
	v_mov_b32_e32 v102, v0
	v_mov_b32_e32 v103, v0
	v_mov_b32_e32 v104, v0
	v_mov_b32_e32 v105, v0
	v_mov_b32_e32 v114, v0
	v_mov_b32_e32 v115, v0
	v_mov_b32_e32 v116, v0
	v_mov_b32_e32 v117, v0
	v_mov_b32_e32 v118, v0
	v_mov_b32_e32 v119, v0
	v_mov_b32_e32 v120, v0
	v_mov_b32_e32 v121, v0
	v_mov_b32_e32 v72, v0
	v_mov_b32_e32 v73, v0
	v_mov_b32_e32 v74, v0
	v_mov_b32_e32 v75, v0
	v_mov_b32_e32 v76, v0
	v_mov_b32_e32 v77, v0
	v_mov_b32_e32 v78, v0
	v_mov_b32_e32 v79, v0
	v_mov_b32_e32 v88, v0
	v_mov_b32_e32 v89, v0
	v_mov_b32_e32 v90, v0
	v_mov_b32_e32 v91, v0
	v_mov_b32_e32 v92, v0
	v_mov_b32_e32 v93, v0
	v_mov_b32_e32 v94, v0
	v_mov_b32_e32 v95, v0
	v_mov_b32_e32 v106, v0
	v_mov_b32_e32 v107, v0
	v_mov_b32_e32 v108, v0
	v_mov_b32_e32 v109, v0
	v_mov_b32_e32 v110, v0
	v_mov_b32_e32 v111, v0
	v_mov_b32_e32 v112, v0
	v_mov_b32_e32 v113, v0
	v_mov_b32_e32 v122, v0
	v_mov_b32_e32 v123, v0
	v_mov_b32_e32 v124, v0
	v_mov_b32_e32 v125, v0
	v_mov_b32_e32 v126, v0
	v_mov_b32_e32 v127, v0
	v_mov_b32_e32 v128, v0
	v_mov_b32_e32 v129, v0
	.p2align 6

; template <class Epi, class Sched, bool ALIGN_EPI = false, bool SP2 = false>
; __device__ __forceinline__ void gemm_phase(PG8_LAS unsigned char* lds, const Gemm g, const Sched& S, const Epi& E, const int tid_in) {
;     ...
; #pragma unroll
;         for (int a = 0; a < 2; ++a)
; #pragma unroll
;             for (int b = 0; b < 2; ++b)
; #pragma unroll
;                 for (int m = 0; m < 4; ++m)
; #pragma unroll
;                     for (int n = 0; n < 2; ++n) acc[a][b][m][n] = (f32x4){0.f, 0.f, 0.f, 0.f};
.LBB0_1922:
	s_add_u32 s55, s12, 0x100
	v_mov_b32_e32 v0, 0
	s_addc_u32 s60, s13, 0
	s_mov_b32 s70, -2
	v_mov_b32_e32 v1, v0
	v_mov_b32_e32 v2, v0
	v_mov_b32_e32 v3, v0
	v_mov_b32_e32 v4, v0
	v_mov_b32_e32 v5, v0
	v_mov_b32_e32 v6, v0
	v_mov_b32_e32 v7, v0
	v_mov_b32_e32 v16, v0
	v_mov_b32_e32 v17, v0
	v_mov_b32_e32 v18, v0
	v_mov_b32_e32 v19, v0
	v_mov_b32_e32 v20, v0
	v_mov_b32_e32 v21, v0
	v_mov_b32_e32 v22, v0
	v_mov_b32_e32 v23, v0
	v_mov_b32_e32 v32, v0
	v_mov_b32_e32 v33, v0
	v_mov_b32_e32 v34, v0
	v_mov_b32_e32 v35, v0
	v_mov_b32_e32 v36, v0
	v_mov_b32_e32 v37, v0
	v_mov_b32_e32 v38, v0
	v_mov_b32_e32 v39, v0
	v_mov_b32_e32 v56, v0
	v_mov_b32_e32 v57, v0
	v_mov_b32_e32 v58, v0
	v_mov_b32_e32 v59, v0
	v_mov_b32_e32 v60, v0
	v_mov_b32_e32 v61, v0
	v_mov_b32_e32 v62, v0
	v_mov_b32_e32 v63, v0
	v_mov_b32_e32 v8, v0
	v_mov_b32_e32 v9, v0
	v_mov_b32_e32 v10, v0
	v_mov_b32_e32 v11, v0
	v_mov_b32_e32 v12, v0
	v_mov_b32_e32 v13, v0
	v_mov_b32_e32 v14, v0
	v_mov_b32_e32 v15, v0
	v_mov_b32_e32 v24, v0
	v_mov_b32_e32 v25, v0
	v_mov_b32_e32 v26, v0
	v_mov_b32_e32 v27, v0
	v_mov_b32_e32 v28, v0
	v_mov_b32_e32 v29, v0
	v_mov_b32_e32 v30, v0
	v_mov_b32_e32 v31, v0
	v_mov_b32_e32 v48, v0
	v_mov_b32_e32 v49, v0
	v_mov_b32_e32 v50, v0
	v_mov_b32_e32 v51, v0
	v_mov_b32_e32 v52, v0
	v_mov_b32_e32 v53, v0
	v_mov_b32_e32 v54, v0
	v_mov_b32_e32 v55, v0
	v_mov_b32_e32 v64, v0
	v_mov_b32_e32 v65, v0
	v_mov_b32_e32 v66, v0
	v_mov_b32_e32 v67, v0
	v_mov_b32_e32 v68, v0
	v_mov_b32_e32 v69, v0
	v_mov_b32_e32 v70, v0
	v_mov_b32_e32 v71, v0
	v_mov_b32_e32 v72, v0
	v_mov_b32_e32 v73, v0
	v_mov_b32_e32 v74, v0
	v_mov_b32_e32 v75, v0
	v_mov_b32_e32 v76, v0
	v_mov_b32_e32 v77, v0
	v_mov_b32_e32 v78, v0
	v_mov_b32_e32 v79, v0
	v_mov_b32_e32 v98, v0
	v_mov_b32_e32 v99, v0
	v_mov_b32_e32 v100, v0
	v_mov_b32_e32 v101, v0
	v_mov_b32_e32 v102, v0
	v_mov_b32_e32 v103, v0
	v_mov_b32_e32 v104, v0
	v_mov_b32_e32 v105, v0
	v_mov_b32_e32 v114, v0
	v_mov_b32_e32 v115, v0
	v_mov_b32_e32 v116, v0
	v_mov_b32_e32 v117, v0
	v_mov_b32_e32 v118, v0
	v_mov_b32_e32 v119, v0
	v_mov_b32_e32 v120, v0
	v_mov_b32_e32 v121, v0
	v_mov_b32_e32 v130, v0
	v_mov_b32_e32 v131, v0
	v_mov_b32_e32 v132, v0
	v_mov_b32_e32 v133, v0
	v_mov_b32_e32 v134, v0
	v_mov_b32_e32 v135, v0
	v_mov_b32_e32 v136, v0
	v_mov_b32_e32 v137, v0
	v_mov_b32_e32 v80, v0
	v_mov_b32_e32 v81, v0
	v_mov_b32_e32 v82, v0
	v_mov_b32_e32 v83, v0
	v_mov_b32_e32 v88, v0
	v_mov_b32_e32 v89, v0
	v_mov_b32_e32 v90, v0
	v_mov_b32_e32 v91, v0
	v_mov_b32_e32 v106, v0
	v_mov_b32_e32 v107, v0
	v_mov_b32_e32 v108, v0
	v_mov_b32_e32 v109, v0
	v_mov_b32_e32 v110, v0
	v_mov_b32_e32 v111, v0
	v_mov_b32_e32 v112, v0
	v_mov_b32_e32 v113, v0
	v_mov_b32_e32 v122, v0
	v_mov_b32_e32 v123, v0
	v_mov_b32_e32 v124, v0
	v_mov_b32_e32 v125, v0
	v_mov_b32_e32 v126, v0
	v_mov_b32_e32 v127, v0
	v_mov_b32_e32 v128, v0
	v_mov_b32_e32 v129, v0
	v_mov_b32_e32 v138, v0
	v_mov_b32_e32 v139, v0
	v_mov_b32_e32 v140, v0
	v_mov_b32_e32 v141, v0
	v_mov_b32_e32 v142, v0
	v_mov_b32_e32 v143, v0
	v_mov_b32_e32 v144, v0
	v_mov_b32_e32 v145, v0
	.p2align 6

; DI void norm_phase(const float* xp, const float* xs, const float* gvec, const float* MODL  , int sc_off, bf16_t* H, int tid,
;                    const float* P, int nparts, const float* pgate, float* X) {
;     ...
;     for (int it = gw; it < M; it += NGW) {
;         const int row = it < MS ? MP + it : it - MS;
;         const int bi = batch_of(row);
;         const float* xr = (row < MP ? xp : xs) + (size_t)row * 1024; const float* mr = MODL + (size_t)bi * NMOD;
.LBB0_1934:
	s_add_i32 s38, s38, s51
	s_mov_b64 s[4:5], 0
	.p2align 6
